# GEMM main loops: LDS-DMA loads use SGPR base + 32-bit VGPR offset form (12 of 16 64-bit VALU address adds per iteration removed)
# speedup vs baseline: 1.0026x; 1.0026x over previous
; #define PG8_STAGE(bufoff, gbase, voff) do { _Pragma("unroll") for (int _i = 0; _i < 2; ++_i) \
;         __builtin_amdgcn_global_load_lds((const unsigned*)((const char*)(gbase) + (voff)[_i]), (PG8_LAS unsigned*)(lds + (bufoff) + ldsw + _i * 8192), 16, 0, 0); } while (0)
; #define PG8_LDA(dst, b, h) do { _Pragma("unroll") for (int m = 0; m < 4; ++m) _Pragma("unroll") for (int k = 0; k < 2; ++k) dst[m][k] = *(const PG8_LAS bf16x8*)(lds + PG8_SA(b, h) + aoff + m * 2048 + k * 1024); } while (0)
; #define PG8_LDB(dst, b, h) do { _Pragma("unroll") for (int n = 0; n < 2; ++n) _Pragma("unroll") for (int k = 0; k < 2; ++k) dst[n][k] = *(const PG8_LAS bf16x8*)(lds + PG8_SB(b, h) + boff + n * 2048 + k * 1024); } while (0)
; #define PG8_MMA(ai, bj, At, Bt) do { __builtin_amdgcn_s_setprio(1); _Pragma("unroll") for (int m = 0; m < 4; ++m) _Pragma("unroll") for (int n = 0; n < 2; ++n) _Pragma("unroll") for (int k = 0; k < 2; ++k) \
;         acc[ai][bj][m][n] = __builtin_amdgcn_mfma_f32_16x16x32_bf16(Bt[n][k], At[m][k], acc[ai][bj][m][n], 0, 0, 0); __builtin_amdgcn_s_setprio(0); } while (0)
; #define PG8_WAIT_V(n) asm volatile("s_waitcnt vmcnt(" #n ")" ::: "memory")
; #define PG8_WAIT_L(n) asm volatile("s_waitcnt lgkmcnt(" #n ")" ::: "memory")
; #define PG8_BAR __builtin_amdgcn_s_barrier()
; #define PG8_SCHED __builtin_amdgcn_sched_barrier(0)
; template <class Epi, class Sched, bool ALIGN_EPI = false, bool SP2 = false>
; __device__ __forceinline__ void gemm_phase(PG8_LAS unsigned char* lds, const Gemm g, const Sched& S, const Epi& E) {
;     ...
;             PG8_LDB(B0, 0, 0); PG8_LDB(B1, 0, 1); PG8_SCHED; PG8_LDA(At, 0, 0); PG8_STAGE(PG8_SA(1, 1), a1 + hstep, voffA);
;             PG8_WAIT_V(8); PG8_WAIT_L(0); PG8_BAR; PG8_MMA(0, 0, At, B0); PG8_MMA(0, 1, At, B1); PG8_BAR; PG8_SCHED;
;             PG8_LDA(At, 0, 1); PG8_STAGE(PG8_SB(0, 0), b2, voffB); PG8_STAGE(PG8_SB(0, 1), b2 + hstep, voffB); PG8_STAGE(PG8_SA(0, 0), a2, voffA);
;             PG8_WAIT_V(8); PG8_WAIT_L(0); PG8_BAR; PG8_MMA(1, 0, At, B0); PG8_MMA(1, 1, At, B1); PG8_BAR; PG8_SCHED;
.LBB0_219:
	s_add_u32 s46, s38, 0xfffc0080
	s_addc_u32 s47, s39, -1
	s_add_i32 s56, 0, 0x10000
	s_cmp_eq_u32 vcc_lo, 12
	s_cselect_b32 s49, s50, s47
	s_cselect_b32 s48, s51, s46
	s_cselect_b32 s47, s52, s73
	s_cselect_b32 s46, s53, s71
	s_add_i32 vcc_hi, 0, 0x14000
	v_add_u32_e32 v152, s56, v165
	v_add_u32_e32 v169, vcc_hi, v165
	ds_read_b128 v[128:131], v152
	ds_read_b128 v[144:147], v152 offset:1024
	ds_read_b128 v[148:151], v152 offset:2048
	ds_read_b128 v[152:155], v152 offset:3072
	ds_read_b128 v[156:159], v169
	ds_read_b128 v[160:163], v169 offset:1024
	ds_read_b128 v[170:173], v169 offset:2048
	ds_read_b128 v[180:183], v169 offset:3072
	s_add_i32 m0, s9, 0xc000
	ds_read_b128 v[184:187], v168
	ds_read_b128 v[188:191], v168 offset:1024
	ds_read_b128 v[192:195], v168 offset:2048
	ds_read_b128 v[196:199], v168 offset:3072
	ds_read_b128 v[200:203], v168 offset:4096
	ds_read_b128 v[204:207], v168 offset:5120
	ds_read_b128 v[218:221], v168 offset:6144
	ds_read_b128 v[222:225], v168 offset:7168
	global_load_lds_dwordx4 v140, s[38:39]
	s_add_i32 m0, s9, 0xe000
	s_nop 0
	global_load_lds_dwordx4 v142, s[38:39]
	s_waitcnt vmcnt(8)
	s_waitcnt lgkmcnt(0)
	s_barrier
	s_setprio 1
	s_waitcnt lgkmcnt(0)
	v_mfma_f32_16x16x32_bf16 v[124:127], v[128:131], v[184:187], v[124:127]
	v_mfma_f32_16x16x32_bf16 v[120:123], v[148:151], v[184:187], v[120:123]
	v_mfma_f32_16x16x32_bf16 v[108:111], v[128:131], v[192:195], v[108:111]
	v_mfma_f32_16x16x32_bf16 v[104:107], v[148:151], v[192:195], v[104:107]
	v_mfma_f32_16x16x32_bf16 v[92:95], v[128:131], v[200:203], v[92:95]
	v_mfma_f32_16x16x32_bf16 v[88:91], v[148:151], v[200:203], v[88:91]
	v_mfma_f32_16x16x32_bf16 v[76:79], v[128:131], v[218:221], v[76:79]
	v_mfma_f32_16x16x32_bf16 v[72:75], v[148:151], v[218:221], v[72:75]
	v_mfma_f32_16x16x32_bf16 v[124:127], v[144:147], v[188:191], v[124:127]
	v_mfma_f32_16x16x32_bf16 v[120:123], v[152:155], v[188:191], v[120:123]
	v_mfma_f32_16x16x32_bf16 v[108:111], v[144:147], v[196:199], v[108:111]
	v_mfma_f32_16x16x32_bf16 v[104:107], v[152:155], v[196:199], v[104:107]
	v_mfma_f32_16x16x32_bf16 v[92:95], v[144:147], v[204:207], v[92:95]
	v_mfma_f32_16x16x32_bf16 v[88:91], v[152:155], v[204:207], v[88:91]
	v_mfma_f32_16x16x32_bf16 v[76:79], v[144:147], v[222:225], v[76:79]
	v_mfma_f32_16x16x32_bf16 v[72:75], v[152:155], v[222:225], v[72:75]
	v_mfma_f32_16x16x32_bf16 v[116:119], v[156:159], v[184:187], v[116:119]
	v_mfma_f32_16x16x32_bf16 v[112:115], v[170:173], v[184:187], v[112:115]
	v_mfma_f32_16x16x32_bf16 v[100:103], v[156:159], v[192:195], v[100:103]
	v_mfma_f32_16x16x32_bf16 v[96:99], v[170:173], v[192:195], v[96:99]
	v_mfma_f32_16x16x32_bf16 v[84:87], v[156:159], v[200:203], v[84:87]
	v_mfma_f32_16x16x32_bf16 v[80:83], v[170:173], v[200:203], v[80:83]
	v_mfma_f32_16x16x32_bf16 v[68:71], v[156:159], v[218:221], v[68:71]
	v_mfma_f32_16x16x32_bf16 v[64:67], v[170:173], v[218:221], v[64:67]
	v_mfma_f32_16x16x32_bf16 v[116:119], v[160:163], v[188:191], v[116:119]
	v_mfma_f32_16x16x32_bf16 v[112:115], v[180:183], v[188:191], v[112:115]
	v_mfma_f32_16x16x32_bf16 v[100:103], v[160:163], v[196:199], v[100:103]
	v_mfma_f32_16x16x32_bf16 v[96:99], v[180:183], v[196:199], v[96:99]
	v_mfma_f32_16x16x32_bf16 v[84:87], v[160:163], v[204:207], v[84:87]
	v_mfma_f32_16x16x32_bf16 v[80:83], v[180:183], v[204:207], v[80:83]
	v_mfma_f32_16x16x32_bf16 v[68:71], v[160:163], v[222:225], v[68:71]
	v_mfma_f32_16x16x32_bf16 v[64:67], v[180:183], v[222:225], v[64:67]
	s_setprio 0
	s_barrier
	s_add_i32 s56, s56, s8
	s_mov_b32 m0, s56
	ds_read_b128 v[184:187], v168 offset:16384
	ds_read_b128 v[188:191], v168 offset:17408
	ds_read_b128 v[192:195], v168 offset:18432
	ds_read_b128 v[196:199], v168 offset:19456
	ds_read_b128 v[200:203], v168 offset:20480
	ds_read_b128 v[204:207], v168 offset:21504
	ds_read_b128 v[218:221], v168 offset:22528
	ds_read_b128 v[222:225], v168 offset:23552
	global_load_lds_dwordx4 v174, s[46:47]
	s_add_i32 m0, s56, 0x2000
	s_add_u32 s56, s46, 0x40000
	s_addc_u32 s57, s47, 0
	s_add_i32 vcc_hi, vcc_hi, s8
	global_load_lds_dwordx4 v136, s[46:47]
	s_mov_b32 m0, vcc_hi
	v_lshl_add_u64 v[226:227], s[48:49], 0, v[134:135]
	global_load_lds_dwordx4 v174, s[56:57]
	s_add_i32 m0, vcc_hi, 0x2000
	s_nop 0
	global_load_lds_dwordx4 v136, s[56:57]
	v_lshl_add_u64 v[208:209], s[48:49], 0, v[132:133]
	s_mov_b32 m0, s9
	s_nop 0
	global_load_lds_dwordx4 v132, s[48:49]
	s_mov_b32 m0, s79
	s_nop 0
	global_load_lds_dwordx4 v134, s[48:49]
	s_waitcnt vmcnt(8)
	s_waitcnt lgkmcnt(0)
	s_barrier
; #define PG8_STAGE(bufoff, gbase, voff) do { _Pragma("unroll") for (int _i = 0; _i < 2; ++_i) \
;         __builtin_amdgcn_global_load_lds((const unsigned*)((const char*)(gbase) + (voff)[_i]), (PG8_LAS unsigned*)(lds + (bufoff) + ldsw + _i * 8192), 16, 0, 0); } while (0)
; #define PG8_LDA(dst, b, h) do { _Pragma("unroll") for (int m = 0; m < 4; ++m) _Pragma("unroll") for (int k = 0; k < 2; ++k) dst[m][k] = *(const PG8_LAS bf16x8*)(lds + PG8_SA(b, h) + aoff + m * 2048 + k * 1024); } while (0)
; #define PG8_LDB(dst, b, h) do { _Pragma("unroll") for (int n = 0; n < 2; ++n) _Pragma("unroll") for (int k = 0; k < 2; ++k) dst[n][k] = *(const PG8_LAS bf16x8*)(lds + PG8_SB(b, h) + boff + n * 2048 + k * 1024); } while (0)
; #define PG8_MMA(ai, bj, At, Bt) do { __builtin_amdgcn_s_setprio(1); _Pragma("unroll") for (int m = 0; m < 4; ++m) _Pragma("unroll") for (int n = 0; n < 2; ++n) _Pragma("unroll") for (int k = 0; k < 2; ++k) \
;         acc[ai][bj][m][n] = __builtin_amdgcn_mfma_f32_16x16x32_bf16(Bt[n][k], At[m][k], acc[ai][bj][m][n], 0, 0, 0); __builtin_amdgcn_s_setprio(0); } while (0)
; #define PG8_WAIT_V(n) asm volatile("s_waitcnt vmcnt(" #n ")" ::: "memory")
; #define PG8_WAIT_L(n) asm volatile("s_waitcnt lgkmcnt(" #n ")" ::: "memory")
; #define PG8_BAR __builtin_amdgcn_s_barrier()
; #define PG8_SCHED __builtin_amdgcn_sched_barrier(0)
; template <class Epi, class Sched, bool ALIGN_EPI = false, bool SP2 = false>
; __device__ __forceinline__ void gemm_phase(PG8_LAS unsigned char* lds, const Gemm g, const Sched& S, const Epi& E) {
;     ...
;             PG8_WAIT_V(8); PG8_WAIT_L(0); PG8_BAR; PG8_MMA(1, 0, At, B0); PG8_MMA(1, 1, At, B1); PG8_BAR; PG8_SCHED;
;             PG8_LDB(B0, 1, 0); PG8_LDB(B1, 1, 1); PG8_SCHED; PG8_LDA(At, 1, 0); PG8_STAGE(PG8_SA(0, 1), a2 + hstep, voffA);
;             PG8_WAIT_V(8); PG8_WAIT_L(0); PG8_BAR; PG8_MMA(0, 0, At, B0); PG8_MMA(0, 1, At, B1); PG8_BAR; PG8_SCHED;
	s_setprio 1
	s_waitcnt lgkmcnt(0)
	v_mfma_f32_16x16x32_bf16 v[60:63], v[128:131], v[184:187], v[60:63]
	v_mfma_f32_16x16x32_bf16 v[56:59], v[148:151], v[184:187], v[56:59]
	v_mfma_f32_16x16x32_bf16 v[44:47], v[128:131], v[192:195], v[44:47]
	v_mfma_f32_16x16x32_bf16 v[40:43], v[148:151], v[192:195], v[40:43]
	v_mfma_f32_16x16x32_bf16 v[28:31], v[128:131], v[200:203], v[28:31]
	v_mfma_f32_16x16x32_bf16 v[24:27], v[148:151], v[200:203], v[24:27]
	v_mfma_f32_16x16x32_bf16 v[12:15], v[128:131], v[218:221], v[12:15]
	v_mfma_f32_16x16x32_bf16 v[8:11], v[148:151], v[218:221], v[8:11]
	v_mfma_f32_16x16x32_bf16 v[60:63], v[144:147], v[188:191], v[60:63]
	v_mfma_f32_16x16x32_bf16 v[56:59], v[152:155], v[188:191], v[56:59]
	v_mfma_f32_16x16x32_bf16 v[44:47], v[144:147], v[196:199], v[44:47]
	v_mfma_f32_16x16x32_bf16 v[40:43], v[152:155], v[196:199], v[40:43]
	v_mfma_f32_16x16x32_bf16 v[28:31], v[144:147], v[204:207], v[28:31]
	v_mfma_f32_16x16x32_bf16 v[24:27], v[152:155], v[204:207], v[24:27]
	v_mfma_f32_16x16x32_bf16 v[12:15], v[144:147], v[222:225], v[12:15]
	v_mfma_f32_16x16x32_bf16 v[8:11], v[152:155], v[222:225], v[8:11]
	v_mfma_f32_16x16x32_bf16 v[52:55], v[156:159], v[184:187], v[52:55]
	v_mfma_f32_16x16x32_bf16 v[48:51], v[170:173], v[184:187], v[48:51]
	v_mfma_f32_16x16x32_bf16 v[36:39], v[156:159], v[192:195], v[36:39]
	v_mfma_f32_16x16x32_bf16 v[32:35], v[170:173], v[192:195], v[32:35]
	v_mfma_f32_16x16x32_bf16 v[20:23], v[156:159], v[200:203], v[20:23]
	v_mfma_f32_16x16x32_bf16 v[16:19], v[170:173], v[200:203], v[16:19]
	v_mfma_f32_16x16x32_bf16 v[4:7], v[156:159], v[218:221], v[4:7]
	v_mfma_f32_16x16x32_bf16 v[0:3], v[170:173], v[218:221], v[0:3]
	v_mfma_f32_16x16x32_bf16 v[52:55], v[160:163], v[188:191], v[52:55]
	v_mfma_f32_16x16x32_bf16 v[48:51], v[180:183], v[188:191], v[48:51]
	v_mfma_f32_16x16x32_bf16 v[36:39], v[160:163], v[196:199], v[36:39]
	v_mfma_f32_16x16x32_bf16 v[32:35], v[180:183], v[196:199], v[32:35]
	v_mfma_f32_16x16x32_bf16 v[20:23], v[160:163], v[204:207], v[20:23]
	v_mfma_f32_16x16x32_bf16 v[16:19], v[180:183], v[204:207], v[16:19]
	v_mfma_f32_16x16x32_bf16 v[4:7], v[160:163], v[222:225], v[4:7]
	v_mfma_f32_16x16x32_bf16 v[0:3], v[180:183], v[222:225], v[0:3]
	s_setprio 0
	s_barrier
	s_add_i32 s56, 0, 0x18000
	s_add_i32 s57, 0, 0x1c000
	v_add_u32_e32 v152, s56, v165
	v_add_u32_e32 v169, s57, v165
	ds_read_b128 v[128:131], v152
	ds_read_b128 v[144:147], v152 offset:1024
	ds_read_b128 v[148:151], v152 offset:2048
	ds_read_b128 v[152:155], v152 offset:3072
	ds_read_b128 v[156:159], v169
	ds_read_b128 v[160:163], v169 offset:1024
	ds_read_b128 v[170:173], v169 offset:2048
	ds_read_b128 v[180:183], v169 offset:3072
	s_add_u32 s48, s48, 0x40000
	s_addc_u32 s49, s49, 0
	s_mov_b32 m0, s54
	ds_read_b128 v[184:187], v168 offset:32768
	ds_read_b128 v[188:191], v168 offset:33792
	ds_read_b128 v[192:195], v168 offset:34816
	ds_read_b128 v[196:199], v168 offset:35840
	ds_read_b128 v[200:203], v168 offset:36864
	ds_read_b128 v[204:207], v168 offset:37888
	ds_read_b128 v[218:221], v168 offset:38912
	ds_read_b128 v[222:225], v168 offset:39936
	global_load_lds_dwordx4 v132, s[48:49]
	s_mov_b32 m0, s55
	s_nop 0
	global_load_lds_dwordx4 v134, s[48:49]
	s_waitcnt vmcnt(8)
	s_waitcnt lgkmcnt(0)
	s_barrier
	s_setprio 1
	s_waitcnt lgkmcnt(0)
	v_mfma_f32_16x16x32_bf16 v[124:127], v[128:131], v[184:187], v[124:127]
	v_mfma_f32_16x16x32_bf16 v[120:123], v[148:151], v[184:187], v[120:123]
	v_mfma_f32_16x16x32_bf16 v[108:111], v[128:131], v[192:195], v[108:111]
	v_mfma_f32_16x16x32_bf16 v[104:107], v[148:151], v[192:195], v[104:107]
	v_mfma_f32_16x16x32_bf16 v[92:95], v[128:131], v[200:203], v[92:95]
	v_mfma_f32_16x16x32_bf16 v[88:91], v[148:151], v[200:203], v[88:91]
	v_mfma_f32_16x16x32_bf16 v[76:79], v[128:131], v[218:221], v[76:79]
	v_mfma_f32_16x16x32_bf16 v[72:75], v[148:151], v[218:221], v[72:75]
	v_mfma_f32_16x16x32_bf16 v[124:127], v[144:147], v[188:191], v[124:127]
	v_mfma_f32_16x16x32_bf16 v[120:123], v[152:155], v[188:191], v[120:123]
	v_mfma_f32_16x16x32_bf16 v[108:111], v[144:147], v[196:199], v[108:111]
	v_mfma_f32_16x16x32_bf16 v[104:107], v[152:155], v[196:199], v[104:107]
	v_mfma_f32_16x16x32_bf16 v[92:95], v[144:147], v[204:207], v[92:95]
	v_mfma_f32_16x16x32_bf16 v[88:91], v[152:155], v[204:207], v[88:91]
	v_mfma_f32_16x16x32_bf16 v[76:79], v[144:147], v[222:225], v[76:79]
	v_mfma_f32_16x16x32_bf16 v[72:75], v[152:155], v[222:225], v[72:75]
	v_mfma_f32_16x16x32_bf16 v[116:119], v[156:159], v[184:187], v[116:119]
	v_mfma_f32_16x16x32_bf16 v[112:115], v[170:173], v[184:187], v[112:115]
	v_mfma_f32_16x16x32_bf16 v[100:103], v[156:159], v[192:195], v[100:103]
	v_mfma_f32_16x16x32_bf16 v[96:99], v[170:173], v[192:195], v[96:99]
	v_mfma_f32_16x16x32_bf16 v[84:87], v[156:159], v[200:203], v[84:87]
	v_mfma_f32_16x16x32_bf16 v[80:83], v[170:173], v[200:203], v[80:83]
	v_mfma_f32_16x16x32_bf16 v[68:71], v[156:159], v[218:221], v[68:71]
	v_mfma_f32_16x16x32_bf16 v[64:67], v[170:173], v[218:221], v[64:67]
	v_mfma_f32_16x16x32_bf16 v[116:119], v[160:163], v[188:191], v[116:119]
	v_mfma_f32_16x16x32_bf16 v[112:115], v[180:183], v[188:191], v[112:115]
	v_mfma_f32_16x16x32_bf16 v[100:103], v[160:163], v[196:199], v[100:103]
	v_mfma_f32_16x16x32_bf16 v[96:99], v[180:183], v[196:199], v[96:99]
	v_mfma_f32_16x16x32_bf16 v[84:87], v[160:163], v[204:207], v[84:87]
	v_mfma_f32_16x16x32_bf16 v[80:83], v[180:183], v[204:207], v[80:83]
	v_mfma_f32_16x16x32_bf16 v[68:71], v[160:163], v[222:225], v[68:71]
	v_mfma_f32_16x16x32_bf16 v[64:67], v[180:183], v[222:225], v[64:67]
	s_setprio 0
	s_barrier
; #define PG8_STAGE(bufoff, gbase, voff) do { _Pragma("unroll") for (int _i = 0; _i < 2; ++_i) \
;         __builtin_amdgcn_global_load_lds((const unsigned*)((const char*)(gbase) + (voff)[_i]), (PG8_LAS unsigned*)(lds + (bufoff) + ldsw + _i * 8192), 16, 0, 0); } while (0)
; #define PG8_LDA(dst, b, h) do { _Pragma("unroll") for (int m = 0; m < 4; ++m) _Pragma("unroll") for (int k = 0; k < 2; ++k) dst[m][k] = *(const PG8_LAS bf16x8*)(lds + PG8_SA(b, h) + aoff + m * 2048 + k * 1024); } while (0)
; #define PG8_MMA(ai, bj, At, Bt) do { __builtin_amdgcn_s_setprio(1); _Pragma("unroll") for (int m = 0; m < 4; ++m) _Pragma("unroll") for (int n = 0; n < 2; ++n) _Pragma("unroll") for (int k = 0; k < 2; ++k) \
;         acc[ai][bj][m][n] = __builtin_amdgcn_mfma_f32_16x16x32_bf16(Bt[n][k], At[m][k], acc[ai][bj][m][n], 0, 0, 0); __builtin_amdgcn_s_setprio(0); } while (0)
; #define PG8_WAIT_V(n) asm volatile("s_waitcnt vmcnt(" #n ")" ::: "memory")
; #define PG8_WAIT_L(n) asm volatile("s_waitcnt lgkmcnt(" #n ")" ::: "memory")
; #define PG8_BAR __builtin_amdgcn_s_barrier()
; #define PG8_SCHED __builtin_amdgcn_sched_barrier(0)
; template <class Epi, class Sched, bool ALIGN_EPI = false, bool SP2 = false>
; __device__ __forceinline__ void gemm_phase(PG8_LAS unsigned char* lds, const Gemm g, const Sched& S, const Epi& E) {
;     ...
;         for (int t = 0; t < nt; t += 2) {
;             const bool last = (t == nt - 2);
;             const char* a1 = cA + (size_t)(t + 1) * kstep;
;             const char* a2 = last ? nA : cA + (size_t)(t + 2) * kstep; const char* b2 = last ? nB : cB + (size_t)(t + 2) * kstep;
;             const char* a3 = a2 + kstep; const char* b3 = b2 + kstep;
;     ...
;             PG8_LDA(At, 1, 1); PG8_STAGE(PG8_SB(1, 0), b3, voffB); PG8_STAGE(PG8_SB(1, 1), b3 + hstep, voffB); PG8_STAGE(PG8_SA(1, 0), a3, voffA);
;             PG8_WAIT_V(8); PG8_WAIT_L(0); PG8_BAR; PG8_MMA(1, 0, At, B0); PG8_MMA(1, 1, At, B1); PG8_BAR; PG8_SCHED;
	s_add_i32 s48, s56, s8
	s_add_u32 s100, s46, s4
	s_addc_u32 s101, s47, s5
	s_mov_b32 m0, s48
	ds_read_b128 v[184:187], v168 offset:49152
	ds_read_b128 v[188:191], v168 offset:50176
	ds_read_b128 v[192:195], v168 offset:51200
	ds_read_b128 v[196:199], v168 offset:52224
	ds_read_b128 v[200:203], v168 offset:53248
	ds_read_b128 v[204:207], v168 offset:54272
	ds_read_b128 v[218:221], v168 offset:55296
	ds_read_b128 v[222:225], v168 offset:56320
	global_load_lds_dwordx4 v174, s[100:101]
	s_add_i32 m0, s48, 0x2000
	s_add_u32 s46, s46, 0x40080
	s_addc_u32 s47, s47, 0
	s_add_i32 s48, s57, s8
	global_load_lds_dwordx4 v136, s[100:101]
	s_mov_b32 m0, s48
	s_nop 0
	global_load_lds_dwordx4 v174, s[46:47]
	s_add_i32 m0, s48, 0x2000
	s_nop 0
	global_load_lds_dwordx4 v136, s[46:47]
	v_lshl_add_u64 v[176:177], v[208:209], 0, s[4:5]
	s_mov_b32 m0, s93
	s_nop 0
	global_load_lds_dwordx4 v[176:177], off
	v_lshl_add_u64 v[176:177], v[226:227], 0, s[4:5]
	s_mov_b32 m0, s66
	s_nop 0
	global_load_lds_dwordx4 v[176:177], off
	s_waitcnt vmcnt(8)
	s_waitcnt lgkmcnt(0)
	s_barrier
	s_setprio 1
	s_waitcnt lgkmcnt(0)
	v_mfma_f32_16x16x32_bf16 v[60:63], v[128:131], v[184:187], v[60:63]
	v_mfma_f32_16x16x32_bf16 v[56:59], v[148:151], v[184:187], v[56:59]
	v_mfma_f32_16x16x32_bf16 v[44:47], v[128:131], v[192:195], v[44:47]
	v_mfma_f32_16x16x32_bf16 v[40:43], v[148:151], v[192:195], v[40:43]
	v_mfma_f32_16x16x32_bf16 v[28:31], v[128:131], v[200:203], v[28:31]
	v_mfma_f32_16x16x32_bf16 v[24:27], v[148:151], v[200:203], v[24:27]
	v_mfma_f32_16x16x32_bf16 v[12:15], v[128:131], v[218:221], v[12:15]
	v_mfma_f32_16x16x32_bf16 v[8:11], v[148:151], v[218:221], v[8:11]
	v_mfma_f32_16x16x32_bf16 v[60:63], v[144:147], v[188:191], v[60:63]
	v_mfma_f32_16x16x32_bf16 v[56:59], v[152:155], v[188:191], v[56:59]
	v_mfma_f32_16x16x32_bf16 v[44:47], v[144:147], v[196:199], v[44:47]
	v_mfma_f32_16x16x32_bf16 v[40:43], v[152:155], v[196:199], v[40:43]
	v_mfma_f32_16x16x32_bf16 v[28:31], v[144:147], v[204:207], v[28:31]
	v_mfma_f32_16x16x32_bf16 v[24:27], v[152:155], v[204:207], v[24:27]
	v_mfma_f32_16x16x32_bf16 v[12:15], v[144:147], v[222:225], v[12:15]
	v_mfma_f32_16x16x32_bf16 v[8:11], v[152:155], v[222:225], v[8:11]
	v_mfma_f32_16x16x32_bf16 v[52:55], v[156:159], v[184:187], v[52:55]
	v_mfma_f32_16x16x32_bf16 v[48:51], v[170:173], v[184:187], v[48:51]
	v_mfma_f32_16x16x32_bf16 v[36:39], v[156:159], v[192:195], v[36:39]
	v_mfma_f32_16x16x32_bf16 v[32:35], v[170:173], v[192:195], v[32:35]
	v_mfma_f32_16x16x32_bf16 v[20:23], v[156:159], v[200:203], v[20:23]
	v_mfma_f32_16x16x32_bf16 v[16:19], v[170:173], v[200:203], v[16:19]
	v_mfma_f32_16x16x32_bf16 v[4:7], v[156:159], v[218:221], v[4:7]
	v_mfma_f32_16x16x32_bf16 v[0:3], v[170:173], v[218:221], v[0:3]
	v_mfma_f32_16x16x32_bf16 v[52:55], v[160:163], v[188:191], v[52:55]
	v_mfma_f32_16x16x32_bf16 v[48:51], v[180:183], v[188:191], v[48:51]
	v_mfma_f32_16x16x32_bf16 v[36:39], v[160:163], v[196:199], v[36:39]
	v_mfma_f32_16x16x32_bf16 v[32:35], v[180:183], v[196:199], v[32:35]
	v_mfma_f32_16x16x32_bf16 v[20:23], v[160:163], v[204:207], v[20:23]
	v_mfma_f32_16x16x32_bf16 v[16:19], v[180:183], v[204:207], v[16:19]
	v_mfma_f32_16x16x32_bf16 v[4:7], v[160:163], v[222:225], v[4:7]
	v_mfma_f32_16x16x32_bf16 v[0:3], v[180:183], v[222:225], v[0:3]
	s_setprio 0
	s_barrier
	s_add_i32 vcc_lo, vcc_lo, 2
	s_add_u32 s38, s38, 0x100
	s_addc_u32 s39, s39, 0
	s_add_u32 s71, s71, 0x100
	s_addc_u32 s73, s73, 0
	s_cmp_gt_u32 vcc_lo, 13
	s_cbranch_scc0 .LBB0_219
	s_and_b64 vcc, exec, s[68:69]
	s_cbranch_vccz .LBB0_222
	s_barrier

; #define PG8_STAGE(bufoff, gbase, voff) do { _Pragma("unroll") for (int _i = 0; _i < 2; ++_i) \
;         __builtin_amdgcn_global_load_lds((const unsigned*)((const char*)(gbase) + (voff)[_i]), (PG8_LAS unsigned*)(lds + (bufoff) + ldsw + _i * 8192), 16, 0, 0); } while (0)
; #define PG8_LDA(dst, b, h) do { _Pragma("unroll") for (int m = 0; m < 4; ++m) _Pragma("unroll") for (int k = 0; k < 2; ++k) dst[m][k] = *(const PG8_LAS bf16x8*)(lds + PG8_SA(b, h) + aoff + m * 2048 + k * 1024); } while (0)
; #define PG8_LDB(dst, b, h) do { _Pragma("unroll") for (int n = 0; n < 2; ++n) _Pragma("unroll") for (int k = 0; k < 2; ++k) dst[n][k] = *(const PG8_LAS bf16x8*)(lds + PG8_SB(b, h) + boff + n * 2048 + k * 1024); } while (0)
; #define PG8_MMA(ai, bj, At, Bt) do { __builtin_amdgcn_s_setprio(1); _Pragma("unroll") for (int m = 0; m < 4; ++m) _Pragma("unroll") for (int n = 0; n < 2; ++n) _Pragma("unroll") for (int k = 0; k < 2; ++k) \
;         acc[ai][bj][m][n] = __builtin_amdgcn_mfma_f32_16x16x32_bf16(Bt[n][k], At[m][k], acc[ai][bj][m][n], 0, 0, 0); __builtin_amdgcn_s_setprio(0); } while (0)
; #define PG8_WAIT_V(n) asm volatile("s_waitcnt vmcnt(" #n ")" ::: "memory")
; #define PG8_WAIT_L(n) asm volatile("s_waitcnt lgkmcnt(" #n ")" ::: "memory")
; #define PG8_BAR __builtin_amdgcn_s_barrier()
; #define PG8_SCHED __builtin_amdgcn_sched_barrier(0)
; template <class Epi, class Sched, bool ALIGN_EPI = false, bool SP2 = false>
; __device__ __forceinline__ void gemm_phase(PG8_LAS unsigned char* lds, const Gemm g, const Sched& S, const Epi& E) {
;     ...
;             PG8_LDB(B0, 0, 0); PG8_LDB(B1, 0, 1); PG8_SCHED; PG8_LDA(At, 0, 0); PG8_STAGE(PG8_SA(1, 1), a1 + hstep, voffA);
;             PG8_WAIT_V(8); PG8_WAIT_L(0); PG8_BAR; PG8_MMA(0, 0, At, B0); PG8_MMA(0, 1, At, B1); PG8_BAR; PG8_SCHED;
;             PG8_LDA(At, 0, 1); PG8_STAGE(PG8_SB(0, 0), b2, voffB); PG8_STAGE(PG8_SB(0, 1), b2 + hstep, voffB); PG8_STAGE(PG8_SA(0, 0), a2, voffA);
;             PG8_WAIT_V(8); PG8_WAIT_L(0); PG8_BAR; PG8_MMA(1, 0, At, B0); PG8_MMA(1, 1, At, B1); PG8_BAR; PG8_SCHED;
;             PG8_LDB(B0, 1, 0); PG8_LDB(B1, 1, 1); PG8_SCHED; PG8_LDA(At, 1, 0); PG8_STAGE(PG8_SA(0, 1), a2 + hstep, voffA);
;             PG8_WAIT_V(8); PG8_WAIT_L(0); PG8_BAR; PG8_MMA(0, 0, At, B0); PG8_MMA(0, 1, At, B1); PG8_BAR; PG8_SCHED;
.LBB0_1752:
	s_add_u32 s38, s0, 0xfffc0080
	s_addc_u32 s39, s1, -1
	s_add_i32 s74, 0, 0x10000
	s_cmp_eq_u32 s73, 12
	s_cselect_b32 s57, s51, s39
	s_cselect_b32 s56, s69, s38
	v_add_u32_e32 v151, s74, v147
	s_cselect_b32 s39, s49, s72
	s_cselect_b32 s38, s70, s71
	s_add_i32 s76, 0, 0x14000
	ds_read_b128 v[138:141], v151
	ds_read_b128 v[142:145], v151 offset:1024
	ds_read_b128 v[152:155], v151 offset:2048
	ds_read_b128 v[156:159], v151 offset:3072
	v_add_u32_e32 v151, s76, v147
	ds_read_b128 v[160:163], v151
	ds_read_b128 v[164:167], v151 offset:1024
	ds_read_b128 v[168:171], v151 offset:2048
	ds_read_b128 v[176:179], v151 offset:3072
	s_add_i32 m0, s58, 0xc000
	ds_read_b128 v[180:183], v150
	ds_read_b128 v[184:187], v150 offset:1024
	ds_read_b128 v[188:191], v150 offset:2048
	ds_read_b128 v[192:195], v150 offset:3072
	ds_read_b128 v[196:199], v150 offset:4096
	ds_read_b128 v[200:203], v150 offset:5120
	ds_read_b128 v[204:207], v150 offset:6144
	ds_read_b128 v[218:221], v150 offset:7168
	global_load_lds_dwordx4 v134, s[0:1]
	s_add_i32 m0, s58, 0xe000
	s_nop 0
	global_load_lds_dwordx4 v136, s[0:1]
	s_waitcnt vmcnt(8)
	s_waitcnt lgkmcnt(0)
	s_barrier
	s_setprio 1
	s_waitcnt lgkmcnt(0)
	v_mfma_f32_16x16x32_bf16 v[124:127], v[138:141], v[180:183], v[124:127]
	v_mfma_f32_16x16x32_bf16 v[120:123], v[152:155], v[180:183], v[120:123]
	v_mfma_f32_16x16x32_bf16 v[108:111], v[138:141], v[188:191], v[108:111]
	v_mfma_f32_16x16x32_bf16 v[104:107], v[152:155], v[188:191], v[104:107]
	v_mfma_f32_16x16x32_bf16 v[92:95], v[138:141], v[196:199], v[92:95]
	v_mfma_f32_16x16x32_bf16 v[88:91], v[152:155], v[196:199], v[88:91]
	v_mfma_f32_16x16x32_bf16 v[76:79], v[138:141], v[204:207], v[76:79]
	v_mfma_f32_16x16x32_bf16 v[72:75], v[152:155], v[204:207], v[72:75]
	v_mfma_f32_16x16x32_bf16 v[124:127], v[142:145], v[184:187], v[124:127]
	v_mfma_f32_16x16x32_bf16 v[120:123], v[156:159], v[184:187], v[120:123]
	v_mfma_f32_16x16x32_bf16 v[108:111], v[142:145], v[192:195], v[108:111]
	v_mfma_f32_16x16x32_bf16 v[104:107], v[156:159], v[192:195], v[104:107]
	v_mfma_f32_16x16x32_bf16 v[92:95], v[142:145], v[200:203], v[92:95]
	v_mfma_f32_16x16x32_bf16 v[88:91], v[156:159], v[200:203], v[88:91]
	v_mfma_f32_16x16x32_bf16 v[76:79], v[142:145], v[218:221], v[76:79]
	v_mfma_f32_16x16x32_bf16 v[72:75], v[156:159], v[218:221], v[72:75]
	v_mfma_f32_16x16x32_bf16 v[116:119], v[160:163], v[180:183], v[116:119]
	v_mfma_f32_16x16x32_bf16 v[112:115], v[168:171], v[180:183], v[112:115]
	v_mfma_f32_16x16x32_bf16 v[100:103], v[160:163], v[188:191], v[100:103]
	v_mfma_f32_16x16x32_bf16 v[96:99], v[168:171], v[188:191], v[96:99]
	v_mfma_f32_16x16x32_bf16 v[84:87], v[160:163], v[196:199], v[84:87]
	v_mfma_f32_16x16x32_bf16 v[80:83], v[168:171], v[196:199], v[80:83]
	v_mfma_f32_16x16x32_bf16 v[68:71], v[160:163], v[204:207], v[68:71]
	v_mfma_f32_16x16x32_bf16 v[64:67], v[168:171], v[204:207], v[64:67]
	v_mfma_f32_16x16x32_bf16 v[116:119], v[164:167], v[184:187], v[116:119]
	v_mfma_f32_16x16x32_bf16 v[112:115], v[176:179], v[184:187], v[112:115]
	v_mfma_f32_16x16x32_bf16 v[100:103], v[164:167], v[192:195], v[100:103]
	v_mfma_f32_16x16x32_bf16 v[96:99], v[176:179], v[192:195], v[96:99]
	v_mfma_f32_16x16x32_bf16 v[84:87], v[164:167], v[200:203], v[84:87]
	v_mfma_f32_16x16x32_bf16 v[80:83], v[176:179], v[200:203], v[80:83]
	v_mfma_f32_16x16x32_bf16 v[68:71], v[164:167], v[218:221], v[68:71]
	v_mfma_f32_16x16x32_bf16 v[64:67], v[176:179], v[218:221], v[64:67]
	s_setprio 0
	s_barrier
	s_add_i32 s74, s74, s8
	s_mov_b32 m0, s74
	ds_read_b128 v[180:183], v150 offset:16384
	ds_read_b128 v[184:187], v150 offset:17408
	ds_read_b128 v[188:191], v150 offset:18432
	ds_read_b128 v[192:195], v150 offset:19456
	ds_read_b128 v[196:199], v150 offset:20480
	ds_read_b128 v[200:203], v150 offset:21504
	ds_read_b128 v[204:207], v150 offset:22528
	ds_read_b128 v[218:221], v150 offset:23552
	global_load_lds_dwordx4 v174, s[38:39]
	s_add_i32 m0, s74, 0x2000
	s_add_u32 s74, s38, 0x40000
	s_addc_u32 s75, s39, 0
	s_add_i32 s76, s76, s8
	global_load_lds_dwordx4 v128, s[38:39]
	s_mov_b32 m0, s76
	v_lshl_add_u64 v[224:225], s[56:57], 0, v[130:131]
	global_load_lds_dwordx4 v174, s[74:75]
	s_add_i32 m0, s76, 0x2000
	s_nop 0
	global_load_lds_dwordx4 v128, s[74:75]
	v_lshl_add_u64 v[222:223], s[56:57], 0, v[132:133]
	s_mov_b32 m0, s58
	s_nop 0
	global_load_lds_dwordx4 v132, s[56:57]
	s_mov_b32 m0, s59
	s_nop 0
	global_load_lds_dwordx4 v130, s[56:57]
	s_waitcnt vmcnt(8)
	s_waitcnt lgkmcnt(0)
	s_barrier
	s_setprio 1
	s_waitcnt lgkmcnt(0)
	v_mfma_f32_16x16x32_bf16 v[60:63], v[138:141], v[180:183], v[60:63]
	v_mfma_f32_16x16x32_bf16 v[56:59], v[152:155], v[180:183], v[56:59]
	v_mfma_f32_16x16x32_bf16 v[44:47], v[138:141], v[188:191], v[44:47]
	v_mfma_f32_16x16x32_bf16 v[40:43], v[152:155], v[188:191], v[40:43]
	v_mfma_f32_16x16x32_bf16 v[28:31], v[138:141], v[196:199], v[28:31]
	v_mfma_f32_16x16x32_bf16 v[24:27], v[152:155], v[196:199], v[24:27]
	v_mfma_f32_16x16x32_bf16 v[12:15], v[138:141], v[204:207], v[12:15]
	v_mfma_f32_16x16x32_bf16 v[8:11], v[152:155], v[204:207], v[8:11]
	v_mfma_f32_16x16x32_bf16 v[60:63], v[142:145], v[184:187], v[60:63]
	v_mfma_f32_16x16x32_bf16 v[56:59], v[156:159], v[184:187], v[56:59]
	v_mfma_f32_16x16x32_bf16 v[44:47], v[142:145], v[192:195], v[44:47]
	v_mfma_f32_16x16x32_bf16 v[40:43], v[156:159], v[192:195], v[40:43]
	v_mfma_f32_16x16x32_bf16 v[28:31], v[142:145], v[200:203], v[28:31]
	v_mfma_f32_16x16x32_bf16 v[24:27], v[156:159], v[200:203], v[24:27]
	v_mfma_f32_16x16x32_bf16 v[12:15], v[142:145], v[218:221], v[12:15]
	v_mfma_f32_16x16x32_bf16 v[8:11], v[156:159], v[218:221], v[8:11]
	v_mfma_f32_16x16x32_bf16 v[52:55], v[160:163], v[180:183], v[52:55]
	v_mfma_f32_16x16x32_bf16 v[48:51], v[168:171], v[180:183], v[48:51]
	v_mfma_f32_16x16x32_bf16 v[36:39], v[160:163], v[188:191], v[36:39]
	v_mfma_f32_16x16x32_bf16 v[32:35], v[168:171], v[188:191], v[32:35]
	v_mfma_f32_16x16x32_bf16 v[20:23], v[160:163], v[196:199], v[20:23]
	v_mfma_f32_16x16x32_bf16 v[16:19], v[168:171], v[196:199], v[16:19]
	v_mfma_f32_16x16x32_bf16 v[4:7], v[160:163], v[204:207], v[4:7]
	v_mfma_f32_16x16x32_bf16 v[0:3], v[168:171], v[204:207], v[0:3]
	v_mfma_f32_16x16x32_bf16 v[52:55], v[164:167], v[184:187], v[52:55]
	v_mfma_f32_16x16x32_bf16 v[48:51], v[176:179], v[184:187], v[48:51]
	v_mfma_f32_16x16x32_bf16 v[36:39], v[164:167], v[192:195], v[36:39]
	v_mfma_f32_16x16x32_bf16 v[32:35], v[176:179], v[192:195], v[32:35]
	v_mfma_f32_16x16x32_bf16 v[20:23], v[164:167], v[200:203], v[20:23]
	v_mfma_f32_16x16x32_bf16 v[16:19], v[176:179], v[200:203], v[16:19]
	v_mfma_f32_16x16x32_bf16 v[4:7], v[164:167], v[218:221], v[4:7]
	v_mfma_f32_16x16x32_bf16 v[0:3], v[176:179], v[218:221], v[0:3]
	s_setprio 0
	s_barrier
; #define PG8_STAGE(bufoff, gbase, voff) do { _Pragma("unroll") for (int _i = 0; _i < 2; ++_i) \
;         __builtin_amdgcn_global_load_lds((const unsigned*)((const char*)(gbase) + (voff)[_i]), (PG8_LAS unsigned*)(lds + (bufoff) + ldsw + _i * 8192), 16, 0, 0); } while (0)
; #define PG8_LDA(dst, b, h) do { _Pragma("unroll") for (int m = 0; m < 4; ++m) _Pragma("unroll") for (int k = 0; k < 2; ++k) dst[m][k] = *(const PG8_LAS bf16x8*)(lds + PG8_SA(b, h) + aoff + m * 2048 + k * 1024); } while (0)
; #define PG8_LDB(dst, b, h) do { _Pragma("unroll") for (int n = 0; n < 2; ++n) _Pragma("unroll") for (int k = 0; k < 2; ++k) dst[n][k] = *(const PG8_LAS bf16x8*)(lds + PG8_SB(b, h) + boff + n * 2048 + k * 1024); } while (0)
; #define PG8_MMA(ai, bj, At, Bt) do { __builtin_amdgcn_s_setprio(1); _Pragma("unroll") for (int m = 0; m < 4; ++m) _Pragma("unroll") for (int n = 0; n < 2; ++n) _Pragma("unroll") for (int k = 0; k < 2; ++k) \
;         acc[ai][bj][m][n] = __builtin_amdgcn_mfma_f32_16x16x32_bf16(Bt[n][k], At[m][k], acc[ai][bj][m][n], 0, 0, 0); __builtin_amdgcn_s_setprio(0); } while (0)
; #define PG8_WAIT_V(n) asm volatile("s_waitcnt vmcnt(" #n ")" ::: "memory")
; #define PG8_WAIT_L(n) asm volatile("s_waitcnt lgkmcnt(" #n ")" ::: "memory")
; #define PG8_BAR __builtin_amdgcn_s_barrier()
; template <class Epi, class Sched, bool ALIGN_EPI = false, bool SP2 = false>
; __device__ __forceinline__ void gemm_phase(PG8_LAS unsigned char* lds, const Gemm g, const Sched& S, const Epi& E) {
;     ...
;         for (int t = 0; t < nt; t += 2) {
;             const bool last = (t == nt - 2);
;             const char* a1 = cA + (size_t)(t + 1) * kstep;
;             const char* a2 = last ? nA : cA + (size_t)(t + 2) * kstep; const char* b2 = last ? nB : cB + (size_t)(t + 2) * kstep;
;             const char* a3 = a2 + kstep; const char* b3 = b2 + kstep;
;     ...
;             PG8_LDB(B0, 1, 0); PG8_LDB(B1, 1, 1); PG8_SCHED; PG8_LDA(At, 1, 0); PG8_STAGE(PG8_SA(0, 1), a2 + hstep, voffA);
;             PG8_WAIT_V(8); PG8_WAIT_L(0); PG8_BAR; PG8_MMA(0, 0, At, B0); PG8_MMA(0, 1, At, B1); PG8_BAR; PG8_SCHED;
;             PG8_LDA(At, 1, 1); PG8_STAGE(PG8_SB(1, 0), b3, voffB); PG8_STAGE(PG8_SB(1, 1), b3 + hstep, voffB); PG8_STAGE(PG8_SA(1, 0), a3, voffA);
;             PG8_WAIT_V(8); PG8_WAIT_L(0); PG8_BAR; PG8_MMA(1, 0, At, B0); PG8_MMA(1, 1, At, B1); PG8_BAR; PG8_SCHED;
	s_add_i32 s74, 0, 0x18000
	v_add_u32_e32 v151, s74, v147
	s_add_i32 s75, 0, 0x1c000
	ds_read_b128 v[138:141], v151
	ds_read_b128 v[142:145], v151 offset:1024
	ds_read_b128 v[152:155], v151 offset:2048
	ds_read_b128 v[156:159], v151 offset:3072
	v_add_u32_e32 v151, s75, v147
	ds_read_b128 v[160:163], v151
	ds_read_b128 v[164:167], v151 offset:1024
	ds_read_b128 v[168:171], v151 offset:2048
	ds_read_b128 v[176:179], v151 offset:3072
	s_add_u32 s56, s56, 0x40000
	s_addc_u32 s57, s57, 0
	s_mov_b32 m0, s60
	ds_read_b128 v[180:183], v150 offset:32768
	ds_read_b128 v[184:187], v150 offset:33792
	ds_read_b128 v[188:191], v150 offset:34816
	ds_read_b128 v[192:195], v150 offset:35840
	ds_read_b128 v[196:199], v150 offset:36864
	ds_read_b128 v[200:203], v150 offset:37888
	ds_read_b128 v[204:207], v150 offset:38912
	ds_read_b128 v[218:221], v150 offset:39936
	global_load_lds_dwordx4 v132, s[56:57]
	s_mov_b32 m0, s61
	s_nop 0
	global_load_lds_dwordx4 v130, s[56:57]
	s_waitcnt vmcnt(8)
	s_waitcnt lgkmcnt(0)
	s_barrier
	s_setprio 1
	s_waitcnt lgkmcnt(0)
	v_mfma_f32_16x16x32_bf16 v[124:127], v[138:141], v[180:183], v[124:127]
	v_mfma_f32_16x16x32_bf16 v[120:123], v[152:155], v[180:183], v[120:123]
	v_mfma_f32_16x16x32_bf16 v[108:111], v[138:141], v[188:191], v[108:111]
	v_mfma_f32_16x16x32_bf16 v[104:107], v[152:155], v[188:191], v[104:107]
	v_mfma_f32_16x16x32_bf16 v[92:95], v[138:141], v[196:199], v[92:95]
	v_mfma_f32_16x16x32_bf16 v[88:91], v[152:155], v[196:199], v[88:91]
	v_mfma_f32_16x16x32_bf16 v[76:79], v[138:141], v[204:207], v[76:79]
	v_mfma_f32_16x16x32_bf16 v[72:75], v[152:155], v[204:207], v[72:75]
	v_mfma_f32_16x16x32_bf16 v[124:127], v[142:145], v[184:187], v[124:127]
	v_mfma_f32_16x16x32_bf16 v[120:123], v[156:159], v[184:187], v[120:123]
	v_mfma_f32_16x16x32_bf16 v[108:111], v[142:145], v[192:195], v[108:111]
	v_mfma_f32_16x16x32_bf16 v[104:107], v[156:159], v[192:195], v[104:107]
	v_mfma_f32_16x16x32_bf16 v[92:95], v[142:145], v[200:203], v[92:95]
	v_mfma_f32_16x16x32_bf16 v[88:91], v[156:159], v[200:203], v[88:91]
	v_mfma_f32_16x16x32_bf16 v[76:79], v[142:145], v[218:221], v[76:79]
	v_mfma_f32_16x16x32_bf16 v[72:75], v[156:159], v[218:221], v[72:75]
	v_mfma_f32_16x16x32_bf16 v[116:119], v[160:163], v[180:183], v[116:119]
	v_mfma_f32_16x16x32_bf16 v[112:115], v[168:171], v[180:183], v[112:115]
	v_mfma_f32_16x16x32_bf16 v[100:103], v[160:163], v[188:191], v[100:103]
	v_mfma_f32_16x16x32_bf16 v[96:99], v[168:171], v[188:191], v[96:99]
	v_mfma_f32_16x16x32_bf16 v[84:87], v[160:163], v[196:199], v[84:87]
	v_mfma_f32_16x16x32_bf16 v[80:83], v[168:171], v[196:199], v[80:83]
	v_mfma_f32_16x16x32_bf16 v[68:71], v[160:163], v[204:207], v[68:71]
	v_mfma_f32_16x16x32_bf16 v[64:67], v[168:171], v[204:207], v[64:67]
	v_mfma_f32_16x16x32_bf16 v[116:119], v[164:167], v[184:187], v[116:119]
	v_mfma_f32_16x16x32_bf16 v[112:115], v[176:179], v[184:187], v[112:115]
	v_mfma_f32_16x16x32_bf16 v[100:103], v[164:167], v[192:195], v[100:103]
	v_mfma_f32_16x16x32_bf16 v[96:99], v[176:179], v[192:195], v[96:99]
	v_mfma_f32_16x16x32_bf16 v[84:87], v[164:167], v[200:203], v[84:87]
	v_mfma_f32_16x16x32_bf16 v[80:83], v[176:179], v[200:203], v[80:83]
	v_mfma_f32_16x16x32_bf16 v[68:71], v[164:167], v[218:221], v[68:71]
	v_mfma_f32_16x16x32_bf16 v[64:67], v[176:179], v[218:221], v[64:67]
	s_setprio 0
	s_barrier
	s_add_i32 s56, s74, s8
	s_add_u32 s100, s38, s4
	s_addc_u32 s101, s39, s5
	s_mov_b32 m0, s56
	ds_read_b128 v[180:183], v150 offset:49152
	ds_read_b128 v[184:187], v150 offset:50176
	ds_read_b128 v[188:191], v150 offset:51200
	ds_read_b128 v[192:195], v150 offset:52224
	ds_read_b128 v[196:199], v150 offset:53248
	ds_read_b128 v[200:203], v150 offset:54272
	ds_read_b128 v[204:207], v150 offset:55296
	ds_read_b128 v[218:221], v150 offset:56320
	global_load_lds_dwordx4 v174, s[100:101]
	s_add_i32 m0, s56, 0x2000
	s_add_u32 s38, s38, 0x40080
	s_addc_u32 s39, s39, 0
	s_add_i32 s56, s75, s8
	global_load_lds_dwordx4 v128, s[100:101]
	s_mov_b32 m0, s56
	s_nop 0
	global_load_lds_dwordx4 v174, s[38:39]
	s_add_i32 m0, s56, 0x2000
	s_nop 0
	global_load_lds_dwordx4 v128, s[38:39]
	v_lshl_add_u64 v[172:173], v[222:223], 0, s[4:5]
	s_mov_b32 m0, s62
	s_nop 0
	global_load_lds_dwordx4 v[172:173], off
	v_lshl_add_u64 v[172:173], v[224:225], 0, s[4:5]
	s_mov_b32 m0, s63
	s_nop 0
	global_load_lds_dwordx4 v[172:173], off
	s_waitcnt vmcnt(8)
	s_waitcnt lgkmcnt(0)
	s_barrier
	s_setprio 1
	s_waitcnt lgkmcnt(0)
	v_mfma_f32_16x16x32_bf16 v[60:63], v[138:141], v[180:183], v[60:63]
	v_mfma_f32_16x16x32_bf16 v[56:59], v[152:155], v[180:183], v[56:59]
	v_mfma_f32_16x16x32_bf16 v[44:47], v[138:141], v[188:191], v[44:47]
	v_mfma_f32_16x16x32_bf16 v[40:43], v[152:155], v[188:191], v[40:43]
	v_mfma_f32_16x16x32_bf16 v[28:31], v[138:141], v[196:199], v[28:31]
	v_mfma_f32_16x16x32_bf16 v[24:27], v[152:155], v[196:199], v[24:27]
	v_mfma_f32_16x16x32_bf16 v[12:15], v[138:141], v[204:207], v[12:15]
	v_mfma_f32_16x16x32_bf16 v[8:11], v[152:155], v[204:207], v[8:11]
	v_mfma_f32_16x16x32_bf16 v[60:63], v[142:145], v[184:187], v[60:63]
	v_mfma_f32_16x16x32_bf16 v[56:59], v[156:159], v[184:187], v[56:59]
	v_mfma_f32_16x16x32_bf16 v[44:47], v[142:145], v[192:195], v[44:47]
	v_mfma_f32_16x16x32_bf16 v[40:43], v[156:159], v[192:195], v[40:43]
	v_mfma_f32_16x16x32_bf16 v[28:31], v[142:145], v[200:203], v[28:31]
	v_mfma_f32_16x16x32_bf16 v[24:27], v[156:159], v[200:203], v[24:27]
	v_mfma_f32_16x16x32_bf16 v[12:15], v[142:145], v[218:221], v[12:15]
	v_mfma_f32_16x16x32_bf16 v[8:11], v[156:159], v[218:221], v[8:11]
	v_mfma_f32_16x16x32_bf16 v[52:55], v[160:163], v[180:183], v[52:55]
	v_mfma_f32_16x16x32_bf16 v[48:51], v[168:171], v[180:183], v[48:51]
	v_mfma_f32_16x16x32_bf16 v[36:39], v[160:163], v[188:191], v[36:39]
	v_mfma_f32_16x16x32_bf16 v[32:35], v[168:171], v[188:191], v[32:35]
	v_mfma_f32_16x16x32_bf16 v[20:23], v[160:163], v[196:199], v[20:23]
	v_mfma_f32_16x16x32_bf16 v[16:19], v[168:171], v[196:199], v[16:19]
	v_mfma_f32_16x16x32_bf16 v[4:7], v[160:163], v[204:207], v[4:7]
	v_mfma_f32_16x16x32_bf16 v[0:3], v[168:171], v[204:207], v[0:3]
	v_mfma_f32_16x16x32_bf16 v[52:55], v[164:167], v[184:187], v[52:55]
	v_mfma_f32_16x16x32_bf16 v[48:51], v[176:179], v[184:187], v[48:51]
	v_mfma_f32_16x16x32_bf16 v[36:39], v[164:167], v[192:195], v[36:39]
	v_mfma_f32_16x16x32_bf16 v[32:35], v[176:179], v[192:195], v[32:35]
	v_mfma_f32_16x16x32_bf16 v[20:23], v[164:167], v[200:203], v[20:23]
	v_mfma_f32_16x16x32_bf16 v[16:19], v[176:179], v[200:203], v[16:19]
	v_mfma_f32_16x16x32_bf16 v[4:7], v[164:167], v[218:221], v[4:7]
	v_mfma_f32_16x16x32_bf16 v[0:3], v[176:179], v[218:221], v[0:3]
	s_setprio 0
	s_barrier
	s_add_i32 s73, s73, 2
	s_add_u32 s0, s0, 0x100
	s_addc_u32 s1, s1, 0
	s_add_u32 s71, s71, 0x100
	s_addc_u32 s72, s72, 0
	s_cmp_gt_u32 s73, 13
	s_cbranch_scc0 .LBB0_1752
	s_and_b64 vcc, exec, s[46:47]
	s_cbranch_vccz .LBB0_1755
	s_barrier

; #define PG8_STAGE(bufoff, gbase, voff) do { _Pragma("unroll") for (int _i = 0; _i < 2; ++_i) \
;         __builtin_amdgcn_global_load_lds((const unsigned*)((const char*)(gbase) + (voff)[_i]), (PG8_LAS unsigned*)(lds + (bufoff) + ldsw + _i * 8192), 16, 0, 0); } while (0)
; #define PG8_LDA(dst, b, h) do { _Pragma("unroll") for (int m = 0; m < 4; ++m) _Pragma("unroll") for (int k = 0; k < 2; ++k) dst[m][k] = *(const PG8_LAS bf16x8*)(lds + PG8_SA(b, h) + aoff + m * 2048 + k * 1024); } while (0)
; #define PG8_LDB(dst, b, h) do { _Pragma("unroll") for (int n = 0; n < 2; ++n) _Pragma("unroll") for (int k = 0; k < 2; ++k) dst[n][k] = *(const PG8_LAS bf16x8*)(lds + PG8_SB(b, h) + boff + n * 2048 + k * 1024); } while (0)
; #define PG8_MMA(ai, bj, At, Bt) do { __builtin_amdgcn_s_setprio(1); _Pragma("unroll") for (int m = 0; m < 4; ++m) _Pragma("unroll") for (int n = 0; n < 2; ++n) _Pragma("unroll") for (int k = 0; k < 2; ++k) \
;         acc[ai][bj][m][n] = __builtin_amdgcn_mfma_f32_16x16x32_bf16(Bt[n][k], At[m][k], acc[ai][bj][m][n], 0, 0, 0); __builtin_amdgcn_s_setprio(0); } while (0)
; #define PG8_WAIT_V(n) asm volatile("s_waitcnt vmcnt(" #n ")" ::: "memory")
; #define PG8_WAIT_L(n) asm volatile("s_waitcnt lgkmcnt(" #n ")" ::: "memory")
; #define PG8_BAR __builtin_amdgcn_s_barrier()
; #define PG8_SCHED __builtin_amdgcn_sched_barrier(0)
; template <class Epi, class Sched, bool ALIGN_EPI = false, bool SP2 = false>
; __device__ __forceinline__ void gemm_phase(PG8_LAS unsigned char* lds, const Gemm g, const Sched& S, const Epi& E) {
;     ...
;             PG8_LDB(B0, 0, 0); PG8_LDB(B1, 0, 1); PG8_SCHED; PG8_LDA(At, 0, 0); PG8_STAGE(PG8_SA(1, 1), a1 + hstep, voffA);
;             PG8_WAIT_V(8); PG8_WAIT_L(0); PG8_BAR; PG8_MMA(0, 0, At, B0); PG8_MMA(0, 1, At, B1); PG8_BAR; PG8_SCHED;
;             PG8_LDA(At, 0, 1); PG8_STAGE(PG8_SB(0, 0), b2, voffB); PG8_STAGE(PG8_SB(0, 1), b2 + hstep, voffB); PG8_STAGE(PG8_SA(0, 0), a2, voffA);
;             PG8_WAIT_V(8); PG8_WAIT_L(0); PG8_BAR; PG8_MMA(1, 0, At, B0); PG8_MMA(1, 1, At, B1); PG8_BAR; PG8_SCHED;
;             PG8_LDB(B0, 1, 0); PG8_LDB(B1, 1, 1); PG8_SCHED; PG8_LDA(At, 1, 0); PG8_STAGE(PG8_SA(0, 1), a2 + hstep, voffA);
;             PG8_WAIT_V(8); PG8_WAIT_L(0); PG8_BAR; PG8_MMA(0, 0, At, B0); PG8_MMA(0, 1, At, B1); PG8_BAR; PG8_SCHED;
.LBB0_1845:
	s_add_u32 s54, s0, 0xfff00080
	s_addc_u32 s55, s1, -1
	s_add_i32 s74, 0, 0x10000
	s_cmp_eq_u32 s73, 60
	s_cselect_b32 s57, s49, s55
	s_cselect_b32 s56, s69, s54
	s_cselect_b32 s55, s47, s72
	s_cselect_b32 s54, s70, s71
	s_add_i32 s76, 0, 0x14000
	v_add_u32_e32 v140, s74, v189
	v_add_u32_e32 v166, s76, v189
	ds_read_b128 v[128:131], v140
	ds_read_b128 v[132:135], v140 offset:1024
	ds_read_b128 v[136:139], v140 offset:2048
	ds_read_b128 v[140:143], v140 offset:3072
	ds_read_b128 v[144:147], v166
	ds_read_b128 v[148:151], v166 offset:1024
	ds_read_b128 v[162:165], v166 offset:2048
	ds_read_b128 v[166:169], v166 offset:3072
	s_add_i32 m0, s59, 0xc000
	ds_read_b128 v[170:173], v191
	ds_read_b128 v[176:179], v191 offset:1024
	ds_read_b128 v[180:183], v191 offset:2048
	ds_read_b128 v[184:187], v191 offset:3072
	ds_read_b128 v[192:195], v191 offset:4096
	ds_read_b128 v[196:199], v191 offset:5120
	ds_read_b128 v[200:203], v191 offset:6144
	ds_read_b128 v[204:207], v191 offset:7168
	global_load_lds_dwordx4 v158, s[0:1]
	s_add_i32 m0, s59, 0xe000
	s_nop 0
	global_load_lds_dwordx4 v160, s[0:1]
	s_waitcnt vmcnt(8)
	s_waitcnt lgkmcnt(0)
	s_barrier
	s_setprio 1
	s_waitcnt lgkmcnt(0)
	v_mfma_f32_16x16x32_bf16 v[124:127], v[128:131], v[170:173], v[124:127]
	v_mfma_f32_16x16x32_bf16 v[120:123], v[136:139], v[170:173], v[120:123]
	v_mfma_f32_16x16x32_bf16 v[108:111], v[128:131], v[180:183], v[108:111]
	v_mfma_f32_16x16x32_bf16 v[104:107], v[136:139], v[180:183], v[104:107]
	v_mfma_f32_16x16x32_bf16 v[92:95], v[128:131], v[192:195], v[92:95]
	v_mfma_f32_16x16x32_bf16 v[88:91], v[136:139], v[192:195], v[88:91]
	v_mfma_f32_16x16x32_bf16 v[76:79], v[128:131], v[200:203], v[76:79]
	v_mfma_f32_16x16x32_bf16 v[72:75], v[136:139], v[200:203], v[72:75]
	v_mfma_f32_16x16x32_bf16 v[124:127], v[132:135], v[176:179], v[124:127]
	v_mfma_f32_16x16x32_bf16 v[120:123], v[140:143], v[176:179], v[120:123]
	v_mfma_f32_16x16x32_bf16 v[108:111], v[132:135], v[184:187], v[108:111]
	v_mfma_f32_16x16x32_bf16 v[104:107], v[140:143], v[184:187], v[104:107]
	v_mfma_f32_16x16x32_bf16 v[92:95], v[132:135], v[196:199], v[92:95]
	v_mfma_f32_16x16x32_bf16 v[88:91], v[140:143], v[196:199], v[88:91]
	v_mfma_f32_16x16x32_bf16 v[76:79], v[132:135], v[204:207], v[76:79]
	v_mfma_f32_16x16x32_bf16 v[72:75], v[140:143], v[204:207], v[72:75]
	v_mfma_f32_16x16x32_bf16 v[116:119], v[144:147], v[170:173], v[116:119]
	v_mfma_f32_16x16x32_bf16 v[112:115], v[162:165], v[170:173], v[112:115]
	v_mfma_f32_16x16x32_bf16 v[100:103], v[144:147], v[180:183], v[100:103]
	v_mfma_f32_16x16x32_bf16 v[96:99], v[162:165], v[180:183], v[96:99]
	v_mfma_f32_16x16x32_bf16 v[84:87], v[144:147], v[192:195], v[84:87]
	v_mfma_f32_16x16x32_bf16 v[80:83], v[162:165], v[192:195], v[80:83]
	v_mfma_f32_16x16x32_bf16 v[68:71], v[144:147], v[200:203], v[68:71]
	v_mfma_f32_16x16x32_bf16 v[64:67], v[162:165], v[200:203], v[64:67]
	v_mfma_f32_16x16x32_bf16 v[116:119], v[148:151], v[176:179], v[116:119]
	v_mfma_f32_16x16x32_bf16 v[112:115], v[166:169], v[176:179], v[112:115]
	v_mfma_f32_16x16x32_bf16 v[100:103], v[148:151], v[184:187], v[100:103]
	v_mfma_f32_16x16x32_bf16 v[96:99], v[166:169], v[184:187], v[96:99]
	v_mfma_f32_16x16x32_bf16 v[84:87], v[148:151], v[196:199], v[84:87]
	v_mfma_f32_16x16x32_bf16 v[80:83], v[166:169], v[196:199], v[80:83]
	v_mfma_f32_16x16x32_bf16 v[68:71], v[148:151], v[204:207], v[68:71]
	v_mfma_f32_16x16x32_bf16 v[64:67], v[166:169], v[204:207], v[64:67]
	s_setprio 0
	s_barrier
	s_add_i32 s74, s74, s58
	s_mov_b32 m0, s74
	ds_read_b128 v[170:173], v191 offset:16384
	ds_read_b128 v[176:179], v191 offset:17408
	ds_read_b128 v[180:183], v191 offset:18432
	ds_read_b128 v[184:187], v191 offset:19456
	ds_read_b128 v[192:195], v191 offset:20480
	ds_read_b128 v[196:199], v191 offset:21504
	ds_read_b128 v[200:203], v191 offset:22528
	ds_read_b128 v[204:207], v191 offset:23552
	global_load_lds_dwordx4 v174, s[54:55]
	s_add_i32 m0, s74, 0x2000
	s_add_u32 s74, s54, 0x100000
	s_addc_u32 s75, s55, 0
	s_add_i32 s76, s76, s58
	global_load_lds_dwordx4 v152, s[54:55]
	s_mov_b32 m0, s76
	v_lshl_add_u64 v[222:223], s[56:57], 0, v[154:155]
	global_load_lds_dwordx4 v174, s[74:75]
	s_add_i32 m0, s76, 0x2000
	s_nop 0
	global_load_lds_dwordx4 v152, s[74:75]
	v_lshl_add_u64 v[220:221], s[56:57], 0, v[156:157]
	s_mov_b32 m0, s59
	s_nop 0
	global_load_lds_dwordx4 v156, s[56:57]
	s_mov_b32 m0, s60
	s_nop 0
	global_load_lds_dwordx4 v154, s[56:57]
	s_waitcnt vmcnt(8)
	s_waitcnt lgkmcnt(0)
	s_barrier
	s_setprio 1
	s_waitcnt lgkmcnt(0)
	v_mfma_f32_16x16x32_bf16 v[60:63], v[128:131], v[170:173], v[60:63]
	v_mfma_f32_16x16x32_bf16 v[56:59], v[136:139], v[170:173], v[56:59]
	v_mfma_f32_16x16x32_bf16 v[44:47], v[128:131], v[180:183], v[44:47]
	v_mfma_f32_16x16x32_bf16 v[40:43], v[136:139], v[180:183], v[40:43]
	v_mfma_f32_16x16x32_bf16 v[28:31], v[128:131], v[192:195], v[28:31]
	v_mfma_f32_16x16x32_bf16 v[24:27], v[136:139], v[192:195], v[24:27]
	v_mfma_f32_16x16x32_bf16 v[12:15], v[128:131], v[200:203], v[12:15]
	v_mfma_f32_16x16x32_bf16 v[8:11], v[136:139], v[200:203], v[8:11]
	v_mfma_f32_16x16x32_bf16 v[60:63], v[132:135], v[176:179], v[60:63]
	v_mfma_f32_16x16x32_bf16 v[56:59], v[140:143], v[176:179], v[56:59]
	v_mfma_f32_16x16x32_bf16 v[44:47], v[132:135], v[184:187], v[44:47]
	v_mfma_f32_16x16x32_bf16 v[40:43], v[140:143], v[184:187], v[40:43]
	v_mfma_f32_16x16x32_bf16 v[28:31], v[132:135], v[196:199], v[28:31]
	v_mfma_f32_16x16x32_bf16 v[24:27], v[140:143], v[196:199], v[24:27]
	v_mfma_f32_16x16x32_bf16 v[12:15], v[132:135], v[204:207], v[12:15]
	v_mfma_f32_16x16x32_bf16 v[8:11], v[140:143], v[204:207], v[8:11]
	v_mfma_f32_16x16x32_bf16 v[52:55], v[144:147], v[170:173], v[52:55]
	v_mfma_f32_16x16x32_bf16 v[48:51], v[162:165], v[170:173], v[48:51]
	v_mfma_f32_16x16x32_bf16 v[36:39], v[144:147], v[180:183], v[36:39]
	v_mfma_f32_16x16x32_bf16 v[32:35], v[162:165], v[180:183], v[32:35]
	v_mfma_f32_16x16x32_bf16 v[20:23], v[144:147], v[192:195], v[20:23]
	v_mfma_f32_16x16x32_bf16 v[16:19], v[162:165], v[192:195], v[16:19]
	v_mfma_f32_16x16x32_bf16 v[4:7], v[144:147], v[200:203], v[4:7]
	v_mfma_f32_16x16x32_bf16 v[0:3], v[162:165], v[200:203], v[0:3]
	v_mfma_f32_16x16x32_bf16 v[52:55], v[148:151], v[176:179], v[52:55]
	v_mfma_f32_16x16x32_bf16 v[48:51], v[166:169], v[176:179], v[48:51]
	v_mfma_f32_16x16x32_bf16 v[36:39], v[148:151], v[184:187], v[36:39]
	v_mfma_f32_16x16x32_bf16 v[32:35], v[166:169], v[184:187], v[32:35]
	v_mfma_f32_16x16x32_bf16 v[20:23], v[148:151], v[196:199], v[20:23]
	v_mfma_f32_16x16x32_bf16 v[16:19], v[166:169], v[196:199], v[16:19]
	v_mfma_f32_16x16x32_bf16 v[4:7], v[148:151], v[204:207], v[4:7]
	v_mfma_f32_16x16x32_bf16 v[0:3], v[166:169], v[204:207], v[0:3]
	s_setprio 0
	s_barrier
; #define PG8_STAGE(bufoff, gbase, voff) do { _Pragma("unroll") for (int _i = 0; _i < 2; ++_i) \
;         __builtin_amdgcn_global_load_lds((const unsigned*)((const char*)(gbase) + (voff)[_i]), (PG8_LAS unsigned*)(lds + (bufoff) + ldsw + _i * 8192), 16, 0, 0); } while (0)
; #define PG8_LDA(dst, b, h) do { _Pragma("unroll") for (int m = 0; m < 4; ++m) _Pragma("unroll") for (int k = 0; k < 2; ++k) dst[m][k] = *(const PG8_LAS bf16x8*)(lds + PG8_SA(b, h) + aoff + m * 2048 + k * 1024); } while (0)
; #define PG8_LDB(dst, b, h) do { _Pragma("unroll") for (int n = 0; n < 2; ++n) _Pragma("unroll") for (int k = 0; k < 2; ++k) dst[n][k] = *(const PG8_LAS bf16x8*)(lds + PG8_SB(b, h) + boff + n * 2048 + k * 1024); } while (0)
; #define PG8_MMA(ai, bj, At, Bt) do { __builtin_amdgcn_s_setprio(1); _Pragma("unroll") for (int m = 0; m < 4; ++m) _Pragma("unroll") for (int n = 0; n < 2; ++n) _Pragma("unroll") for (int k = 0; k < 2; ++k) \
;         acc[ai][bj][m][n] = __builtin_amdgcn_mfma_f32_16x16x32_bf16(Bt[n][k], At[m][k], acc[ai][bj][m][n], 0, 0, 0); __builtin_amdgcn_s_setprio(0); } while (0)
; #define PG8_WAIT_V(n) asm volatile("s_waitcnt vmcnt(" #n ")" ::: "memory")
; #define PG8_WAIT_L(n) asm volatile("s_waitcnt lgkmcnt(" #n ")" ::: "memory")
; #define PG8_BAR __builtin_amdgcn_s_barrier()
; template <class Epi, class Sched, bool ALIGN_EPI = false, bool SP2 = false>
; __device__ __forceinline__ void gemm_phase(PG8_LAS unsigned char* lds, const Gemm g, const Sched& S, const Epi& E) {
;     ...
;         for (int t = 0; t < nt; t += 2) {
;             const bool last = (t == nt - 2);
;             const char* a1 = cA + (size_t)(t + 1) * kstep;
;             const char* a2 = last ? nA : cA + (size_t)(t + 2) * kstep; const char* b2 = last ? nB : cB + (size_t)(t + 2) * kstep;
;             const char* a3 = a2 + kstep; const char* b3 = b2 + kstep;
;     ...
;             PG8_LDB(B0, 1, 0); PG8_LDB(B1, 1, 1); PG8_SCHED; PG8_LDA(At, 1, 0); PG8_STAGE(PG8_SA(0, 1), a2 + hstep, voffA);
;             PG8_WAIT_V(8); PG8_WAIT_L(0); PG8_BAR; PG8_MMA(0, 0, At, B0); PG8_MMA(0, 1, At, B1); PG8_BAR; PG8_SCHED;
;             PG8_LDA(At, 1, 1); PG8_STAGE(PG8_SB(1, 0), b3, voffB); PG8_STAGE(PG8_SB(1, 1), b3 + hstep, voffB); PG8_STAGE(PG8_SA(1, 0), a3, voffA);
;             PG8_WAIT_V(8); PG8_WAIT_L(0); PG8_BAR; PG8_MMA(1, 0, At, B0); PG8_MMA(1, 1, At, B1); PG8_BAR; PG8_SCHED;
	s_add_i32 s74, 0, 0x18000
	s_add_i32 s75, 0, 0x1c000
	v_add_u32_e32 v140, s74, v189
	v_add_u32_e32 v166, s75, v189
	ds_read_b128 v[128:131], v140
	ds_read_b128 v[132:135], v140 offset:1024
	ds_read_b128 v[136:139], v140 offset:2048
	ds_read_b128 v[140:143], v140 offset:3072
	ds_read_b128 v[144:147], v166
	ds_read_b128 v[148:151], v166 offset:1024
	ds_read_b128 v[162:165], v166 offset:2048
	ds_read_b128 v[166:169], v166 offset:3072
	s_add_u32 s56, s56, 0x100000
	s_addc_u32 s57, s57, 0
	s_mov_b32 m0, s61
	ds_read_b128 v[170:173], v191 offset:32768
	ds_read_b128 v[176:179], v191 offset:33792
	ds_read_b128 v[180:183], v191 offset:34816
	ds_read_b128 v[184:187], v191 offset:35840
	ds_read_b128 v[192:195], v191 offset:36864
	ds_read_b128 v[196:199], v191 offset:37888
	ds_read_b128 v[200:203], v191 offset:38912
	ds_read_b128 v[204:207], v191 offset:39936
	global_load_lds_dwordx4 v156, s[56:57]
	s_mov_b32 m0, s62
	s_nop 0
	global_load_lds_dwordx4 v154, s[56:57]
	s_waitcnt vmcnt(8)
	s_waitcnt lgkmcnt(0)
	s_barrier
	s_setprio 1
	s_waitcnt lgkmcnt(0)
	v_mfma_f32_16x16x32_bf16 v[124:127], v[128:131], v[170:173], v[124:127]
	v_mfma_f32_16x16x32_bf16 v[120:123], v[136:139], v[170:173], v[120:123]
	v_mfma_f32_16x16x32_bf16 v[108:111], v[128:131], v[180:183], v[108:111]
	v_mfma_f32_16x16x32_bf16 v[104:107], v[136:139], v[180:183], v[104:107]
	v_mfma_f32_16x16x32_bf16 v[92:95], v[128:131], v[192:195], v[92:95]
	v_mfma_f32_16x16x32_bf16 v[88:91], v[136:139], v[192:195], v[88:91]
	v_mfma_f32_16x16x32_bf16 v[76:79], v[128:131], v[200:203], v[76:79]
	v_mfma_f32_16x16x32_bf16 v[72:75], v[136:139], v[200:203], v[72:75]
	v_mfma_f32_16x16x32_bf16 v[124:127], v[132:135], v[176:179], v[124:127]
	v_mfma_f32_16x16x32_bf16 v[120:123], v[140:143], v[176:179], v[120:123]
	v_mfma_f32_16x16x32_bf16 v[108:111], v[132:135], v[184:187], v[108:111]
	v_mfma_f32_16x16x32_bf16 v[104:107], v[140:143], v[184:187], v[104:107]
	v_mfma_f32_16x16x32_bf16 v[92:95], v[132:135], v[196:199], v[92:95]
	v_mfma_f32_16x16x32_bf16 v[88:91], v[140:143], v[196:199], v[88:91]
	v_mfma_f32_16x16x32_bf16 v[76:79], v[132:135], v[204:207], v[76:79]
	v_mfma_f32_16x16x32_bf16 v[72:75], v[140:143], v[204:207], v[72:75]
	v_mfma_f32_16x16x32_bf16 v[116:119], v[144:147], v[170:173], v[116:119]
	v_mfma_f32_16x16x32_bf16 v[112:115], v[162:165], v[170:173], v[112:115]
	v_mfma_f32_16x16x32_bf16 v[100:103], v[144:147], v[180:183], v[100:103]
	v_mfma_f32_16x16x32_bf16 v[96:99], v[162:165], v[180:183], v[96:99]
	v_mfma_f32_16x16x32_bf16 v[84:87], v[144:147], v[192:195], v[84:87]
	v_mfma_f32_16x16x32_bf16 v[80:83], v[162:165], v[192:195], v[80:83]
	v_mfma_f32_16x16x32_bf16 v[68:71], v[144:147], v[200:203], v[68:71]
	v_mfma_f32_16x16x32_bf16 v[64:67], v[162:165], v[200:203], v[64:67]
	v_mfma_f32_16x16x32_bf16 v[116:119], v[148:151], v[176:179], v[116:119]
	v_mfma_f32_16x16x32_bf16 v[112:115], v[166:169], v[176:179], v[112:115]
	v_mfma_f32_16x16x32_bf16 v[100:103], v[148:151], v[184:187], v[100:103]
	v_mfma_f32_16x16x32_bf16 v[96:99], v[166:169], v[184:187], v[96:99]
	v_mfma_f32_16x16x32_bf16 v[84:87], v[148:151], v[196:199], v[84:87]
	v_mfma_f32_16x16x32_bf16 v[80:83], v[166:169], v[196:199], v[80:83]
	v_mfma_f32_16x16x32_bf16 v[68:71], v[148:151], v[204:207], v[68:71]
	v_mfma_f32_16x16x32_bf16 v[64:67], v[166:169], v[204:207], v[64:67]
	s_setprio 0
	s_barrier
	s_add_i32 s56, s74, s58
	s_add_u32 s100, s54, s4
	s_addc_u32 s101, s55, s5
	s_mov_b32 m0, s56
	ds_read_b128 v[170:173], v191 offset:49152
	ds_read_b128 v[176:179], v191 offset:50176
	ds_read_b128 v[180:183], v191 offset:51200
	ds_read_b128 v[184:187], v191 offset:52224
	ds_read_b128 v[192:195], v191 offset:53248
	ds_read_b128 v[196:199], v191 offset:54272
	ds_read_b128 v[200:203], v191 offset:55296
	ds_read_b128 v[204:207], v191 offset:56320
	global_load_lds_dwordx4 v174, s[100:101]
	s_add_i32 m0, s56, 0x2000
	s_add_u32 s54, s54, 0x100080
	s_addc_u32 s55, s55, 0
	s_add_i32 s56, s75, s58
	global_load_lds_dwordx4 v152, s[100:101]
	s_mov_b32 m0, s56
	s_nop 0
	global_load_lds_dwordx4 v174, s[54:55]
	s_add_i32 m0, s56, 0x2000
	s_nop 0
	global_load_lds_dwordx4 v152, s[54:55]
	v_lshl_add_u64 v[208:209], v[220:221], 0, s[4:5]
	s_mov_b32 m0, s64
	s_nop 0
	global_load_lds_dwordx4 v[208:209], off
	v_lshl_add_u64 v[208:209], v[222:223], 0, s[4:5]
	s_mov_b32 m0, s65
	s_nop 0
	global_load_lds_dwordx4 v[208:209], off
	s_waitcnt vmcnt(8)
	s_waitcnt lgkmcnt(0)
	s_barrier
	s_setprio 1
	s_waitcnt lgkmcnt(0)
	v_mfma_f32_16x16x32_bf16 v[60:63], v[128:131], v[170:173], v[60:63]
	v_mfma_f32_16x16x32_bf16 v[56:59], v[136:139], v[170:173], v[56:59]
	v_mfma_f32_16x16x32_bf16 v[44:47], v[128:131], v[180:183], v[44:47]
	v_mfma_f32_16x16x32_bf16 v[40:43], v[136:139], v[180:183], v[40:43]
	v_mfma_f32_16x16x32_bf16 v[28:31], v[128:131], v[192:195], v[28:31]
	v_mfma_f32_16x16x32_bf16 v[24:27], v[136:139], v[192:195], v[24:27]
	v_mfma_f32_16x16x32_bf16 v[12:15], v[128:131], v[200:203], v[12:15]
	v_mfma_f32_16x16x32_bf16 v[8:11], v[136:139], v[200:203], v[8:11]
	v_mfma_f32_16x16x32_bf16 v[60:63], v[132:135], v[176:179], v[60:63]
	v_mfma_f32_16x16x32_bf16 v[56:59], v[140:143], v[176:179], v[56:59]
	v_mfma_f32_16x16x32_bf16 v[44:47], v[132:135], v[184:187], v[44:47]
	v_mfma_f32_16x16x32_bf16 v[40:43], v[140:143], v[184:187], v[40:43]
	v_mfma_f32_16x16x32_bf16 v[28:31], v[132:135], v[196:199], v[28:31]
	v_mfma_f32_16x16x32_bf16 v[24:27], v[140:143], v[196:199], v[24:27]
	v_mfma_f32_16x16x32_bf16 v[12:15], v[132:135], v[204:207], v[12:15]
	v_mfma_f32_16x16x32_bf16 v[8:11], v[140:143], v[204:207], v[8:11]
	v_mfma_f32_16x16x32_bf16 v[52:55], v[144:147], v[170:173], v[52:55]
	v_mfma_f32_16x16x32_bf16 v[48:51], v[162:165], v[170:173], v[48:51]
	v_mfma_f32_16x16x32_bf16 v[36:39], v[144:147], v[180:183], v[36:39]
	v_mfma_f32_16x16x32_bf16 v[32:35], v[162:165], v[180:183], v[32:35]
	v_mfma_f32_16x16x32_bf16 v[20:23], v[144:147], v[192:195], v[20:23]
	v_mfma_f32_16x16x32_bf16 v[16:19], v[162:165], v[192:195], v[16:19]
	v_mfma_f32_16x16x32_bf16 v[4:7], v[144:147], v[200:203], v[4:7]
	v_mfma_f32_16x16x32_bf16 v[0:3], v[162:165], v[200:203], v[0:3]
	v_mfma_f32_16x16x32_bf16 v[52:55], v[148:151], v[176:179], v[52:55]
	v_mfma_f32_16x16x32_bf16 v[48:51], v[166:169], v[176:179], v[48:51]
	v_mfma_f32_16x16x32_bf16 v[36:39], v[148:151], v[184:187], v[36:39]
	v_mfma_f32_16x16x32_bf16 v[32:35], v[166:169], v[184:187], v[32:35]
	v_mfma_f32_16x16x32_bf16 v[20:23], v[148:151], v[196:199], v[20:23]
	v_mfma_f32_16x16x32_bf16 v[16:19], v[166:169], v[196:199], v[16:19]
	v_mfma_f32_16x16x32_bf16 v[4:7], v[148:151], v[204:207], v[4:7]
	v_mfma_f32_16x16x32_bf16 v[0:3], v[166:169], v[204:207], v[0:3]
	s_setprio 0
	s_barrier
	s_add_i32 s73, s73, 2
	s_add_u32 s0, s0, 0x100
	s_addc_u32 s1, s1, 0
	s_add_u32 s71, s71, 0x100
	s_addc_u32 s72, s72, 0
	s_cmp_gt_u32 s73, 61
	s_cbranch_scc0 .LBB0_1845
	s_and_b64 vcc, exec, s[38:39]
	s_cbranch_vccz .LBB0_1848
	s_barrier

; #define LAS __attribute__((address_space(3)))
; __global__ void __launch_bounds__(NTHREADS, 2) fwd_kernel(Args a) {
;     extern __shared__ __attribute__((aligned(16))) unsigned char lds_raw[];
;     LAS unsigned char* lds = (LAS unsigned char*)lds_raw;
	.amdhsa_kernel _Z10fwd_kernel4Args
		.amdhsa_group_segment_fixed_size 0
		.amdhsa_private_segment_fixed_size 0
		.amdhsa_kernarg_size 400
		.amdhsa_user_sgpr_count 2
		.amdhsa_user_sgpr_dispatch_ptr 0
		.amdhsa_user_sgpr_queue_ptr 0
		.amdhsa_user_sgpr_kernarg_segment_ptr 1
		.amdhsa_user_sgpr_dispatch_id 0
		.amdhsa_user_sgpr_kernarg_preload_length 0
		.amdhsa_user_sgpr_kernarg_preload_offset 0
		.amdhsa_user_sgpr_private_segment_size 0
		.amdhsa_uses_dynamic_stack 0
		.amdhsa_enable_private_segment 0
		.amdhsa_system_sgpr_workgroup_id_x 1
		.amdhsa_system_sgpr_workgroup_id_y 0
		.amdhsa_system_sgpr_workgroup_id_z 0
		.amdhsa_system_sgpr_workgroup_info 0
		.amdhsa_system_vgpr_workitem_id 2
		.amdhsa_next_free_vgpr 256
		.amdhsa_next_free_sgpr 102
		.amdhsa_accum_offset 256
		.amdhsa_reserve_vcc 1
		.amdhsa_float_round_mode_32 0
		.amdhsa_float_round_mode_16_64 0
		.amdhsa_float_denorm_mode_32 3
		.amdhsa_float_denorm_mode_16_64 3
		.amdhsa_dx10_clamp 1
		.amdhsa_ieee_mode 1
		.amdhsa_fp16_overflow 0
		.amdhsa_tg_split 0
		.amdhsa_exception_fp_ieee_invalid_op 0
		.amdhsa_exception_fp_denorm_src 0
		.amdhsa_exception_fp_ieee_div_zero 0
		.amdhsa_exception_fp_ieee_overflow 0
		.amdhsa_exception_fp_ieee_underflow 0
		.amdhsa_exception_fp_ieee_inexact 0
		.amdhsa_exception_int_div_zero 0
	.end_amdhsa_kernel

; #define LAS __attribute__((address_space(3)))
; __global__ void __launch_bounds__(NTHREADS, 2) fwd_kernel(Args a) {
;     extern __shared__ __attribute__((aligned(16))) unsigned char lds_raw[];
;     LAS unsigned char* lds = (LAS unsigned char*)lds_raw;
amdhsa.kernels:
  - .agpr_count:     0
    .args:
      - .offset:         0
        .size:           144
        .value_kind:     by_value
      - .offset:         144
        .size:           4
        .value_kind:     hidden_block_count_x
      - .offset:         148
        .size:           4
        .value_kind:     hidden_block_count_y
      - .offset:         152
        .size:           4
        .value_kind:     hidden_block_count_z
      - .offset:         156
        .size:           2
        .value_kind:     hidden_group_size_x
      - .offset:         158
        .size:           2
        .value_kind:     hidden_group_size_y
      - .offset:         160
        .size:           2
        .value_kind:     hidden_group_size_z
      - .offset:         162
        .size:           2
        .value_kind:     hidden_remainder_x
      - .offset:         164
        .size:           2
        .value_kind:     hidden_remainder_y
      - .offset:         166
        .size:           2
        .value_kind:     hidden_remainder_z
      - .offset:         184
        .size:           8
        .value_kind:     hidden_global_offset_x
      - .offset:         192
        .size:           8
        .value_kind:     hidden_global_offset_y
      - .offset:         200
        .size:           8
        .value_kind:     hidden_global_offset_z
      - .offset:         208
        .size:           2
        .value_kind:     hidden_grid_dims
      - .offset:         232
        .size:           8
        .value_kind:     hidden_multigrid_sync_arg
      - .offset:         264
        .size:           4
        .value_kind:     hidden_dynamic_lds_size
    .group_segment_fixed_size: 0
    .kernarg_segment_align: 8
    .kernarg_segment_size: 400
    .language:       OpenCL C
    .language_version:
      - 2
      - 0
    .max_flat_workgroup_size: 512
    .name:           _Z10fwd_kernel4Args
    .private_segment_fixed_size: 0
    .sgpr_count:     108
    .sgpr_spill_count: 212
    .symbol:         _Z10fwd_kernel4Args.kd
    .uniform_work_group_size: 1
    .uses_dynamic_stack: false
    .vgpr_count:     256
    .vgpr_spill_count: 0
    .wavefront_size: 64
